# as v20 plus: no per-call acquire for kind 2 (first-touch data only), nt hint on the final f32 output stores
# speedup vs baseline: 1.0073x; 1.0049x over previous
.LBB0_377:
	s_or_b64 exec, exec, s[72:73]
	s_add_u32 s6, s68, 0xb300000
	v_mov_b32_e32 v2, v0
	s_addc_u32 s7, s69, 0
	s_barrier
	s_lshl_b32 s9, s17, 14
	v_ashrrev_i32_e32 v4, 1, v2
	v_ashrrev_i32_e32 v5, 31, v4
	s_add_u32 s18, s6, s9
	v_and_b32_e32 v11, 1, v2
	s_addc_u32 s19, s7, 0
	s_waitcnt vmcnt(18)
	v_lshlrev_b64 v[12:13], 6, v[4:5]
	v_lshl_add_u64 v[12:13], s[18:19], 0, v[12:13]
	v_lshlrev_b32_e32 v2, 5, v11
	s_waitcnt vmcnt(10)
	v_lshl_add_u64 v[20:21], v[12:13], 0, v[2:3]
	global_load_dwordx4 v[12:15], v[20:21], off sc1
	global_load_dwordx4 v[16:19], v[20:21], off offset:16 sc1
	s_waitcnt lgkmcnt(0)
	s_add_u32 s9, s66, 0x2a00000
	s_addc_u32 s18, s67, 0
	s_lshl_b32 s19, s17, 19
	s_add_u32 s66, s9, s19
	s_addc_u32 s67, s18, 0
	v_lshl_add_u32 v136, v7, 11, v8
	s_add_i32 m0, s16, 0
	s_nop 0
	global_load_lds_dwordx4 v136, s[66:67]
	s_ashr_i32 s33, s29, 8
	v_lshl_add_u32 v137, v9, 11, v10
	s_add_i32 m0, s16, 0x2000
	s_nop 0
	global_load_lds_dwordx4 v137, s[66:67]
	s_add_u32 s38, s66, 0x40000
	s_addc_u32 s39, s67, 0
	s_add_i32 m0, s16, 0x4000
	s_nop 0
	global_load_lds_dwordx4 v136, s[38:39]
	s_nop 0
	s_add_i32 m0, s16, 0x6000
	s_nop 0
	global_load_lds_dwordx4 v137, s[38:39]
	s_waitcnt vmcnt(4)
	s_nop 0
	v_add_f32_e32 v2, v12, v13
	v_add_f32_e32 v5, v14, v15
	v_add_f32_e32 v2, v2, v5
	v_add_f32_e32 v5, v16, v17
	v_add_f32_e32 v12, v18, v19
	v_add_f32_e32 v5, v5, v12
	v_and_b32_e32 v12, 64, v192
	v_add_f32_e32 v2, v2, v5
	v_xor_b32_e32 v5, 1, v192
	v_add_u32_e32 v12, 64, v12
	v_cmp_lt_i32_e32 vcc, v5, v12
	s_nop 1
	v_cndmask_b32_e32 v5, v192, v5, vcc
	v_lshlrev_b32_e32 v135, 2, v5
	ds_bpermute_b32 v5, v135, v2
	v_cmp_eq_u32_e32 vcc, 0, v11
	s_and_saveexec_b64 s[68:69], vcc
	s_cbranch_execz .LBB0_379
	s_waitcnt lgkmcnt(0)
	v_add_f32_e32 v2, v2, v5
	v_fmamk_f32 v2, v2, 0x3a800000, v254
	s_lshl_b32 s32, s17, 8
	v_rsq_f32_e32 v5, v2
	s_and_b32 s32, s32, 0x400
	s_add_i32 s32, s32, 0
	v_lshl_add_u32 v4, v4, 2, s32
	v_add_u32_e32 v4, 0x24400, v4
	ds_write2st64_b32 v4, v5, v2 offset1:8

.LBB0_691:
	s_or_b64 exec, exec, s[2:3]
	s_andn2_b64 vcc, exec, s[70:71]
	s_cbranch_vccnz .LBB0_693
	s_cmp_eq_u32 s42, 2
	s_cbranch_scc1 .LBB0_693
	s_waitcnt vmcnt(0)
	buffer_inv sc1
	s_waitcnt vmcnt(0)

.LBB0_875:
	s_waitcnt lgkmcnt(0)
	s_mov_b64 s[2:3], s[0:1]
	s_barrier
	s_load_dwordx2 s[2:3], s[2:3], 0x88
	v_lshlrev_b32_e32 v2, 3, v167
	s_mov_b64 s[14:15], s[0:1]
	s_ashr_i32 s9, s8, 31
	v_mov_b32_e32 v4, v2
	s_lshl_b64 s[12:13], s[12:13], 2
	s_load_dwordx2 s[14:15], s[14:15], 0x90
	s_waitcnt lgkmcnt(0)
	s_add_u32 s2, s2, s12
	v_ashrrev_i32_e32 v5, 31, v4
	s_addc_u32 s3, s3, s13
	v_lshlrev_b64 v[74:75], 2, v[4:5]
	v_and_b32_e32 v2, 0x80, v2
	v_and_or_b32 v76, v1, 14, s8
	v_mov_b32_e32 v77, s9
	v_lshl_add_u64 v[8:9], s[2:3], 0, v[74:75]
	v_ashrrev_i32_e32 v167, 31, v166
	v_lshl_add_u64 v[76:77], v[76:77], 0, v[2:3]
	s_lshl_b64 s[2:3], s[66:67], 14
	v_lshl_add_u64 v[76:77], v[76:77], 0, v[166:167]
	s_add_u32 s2, s6, s2
	v_lshlrev_b64 v[76:77], 6, v[76:77]
	s_addc_u32 s3, s7, s3
	v_lshlrev_b32_e32 v2, 5, v1
	v_lshl_add_u64 v[76:77], s[2:3], 0, v[76:77]
	v_and_b32_e32 v2, 32, v2
	v_lshl_add_u64 v[76:77], v[76:77], 0, v[2:3]
	global_load_dwordx4 v[4:7], v[8:9], off offset:16
	s_nop 0
	global_load_dwordx4 v[8:11], v[8:9], off
	s_nop 0
	global_load_dword v2, v[76:77], off sc1
	s_nop 0
	global_load_dword v76, v[76:77], off offset:16 sc1
	v_and_b32_e32 v1, 32, v1
	v_and_or_b32 v1, v192, 64, v1
	v_lshlrev_b32_e32 v1, 2, v1
	s_lshl_b64 s[2:3], s[66:67], 20
	s_add_u32 s2, s14, s2
	s_addc_u32 s3, s15, s3
	s_waitcnt vmcnt(0)
	v_add_f32_e32 v2, v76, v2
	s_nop 1
	v_add_f32_dpp v2, v2, v2 quad_perm:[1,0,3,2] row_mask:0xf bank_mask:0xf bound_ctrl:1
	v_fmamk_f32 v2, v2, 0x3a800000, v254
	v_rsq_f32_e32 v2, v2
	v_lshl_add_u64 v[76:77], v[166:167], 0, s[8:9]
	v_lshlrev_b64 v[76:77], 12, v[76:77]
	v_lshl_add_u64 v[76:77], s[2:3], 0, v[76:77]
	ds_bpermute_b32 v80, v1, v2
	v_lshl_add_u64 v[76:77], v[76:77], 0, s[12:13]
	v_lshl_add_u64 v[74:75], v[76:77], 0, v[74:75]
	s_mov_b64 s[2:3], 0x2000
	v_lshl_add_u64 v[82:83], v[74:75], 0, s[2:3]
	s_waitcnt lgkmcnt(0)
	v_pk_mul_f32 v[76:77], v[180:181], v[80:81] op_sel_hi:[1,0]
	v_pk_mul_f32 v[78:79], v[178:179], v[80:81] op_sel_hi:[1,0]
	v_pk_mul_f32 v[76:77], v[8:9], v[76:77]
	v_pk_mul_f32 v[78:79], v[10:11], v[78:79]
	global_store_dwordx4 v[74:75], v[76:79], off nt
	s_movk_i32 s2, 0x2000
	v_add_co_u32_e32 v84, vcc, s2, v74
	v_pk_mul_f32 v[76:77], v[182:183], v[80:81] op_sel_hi:[1,0]
	v_pk_mul_f32 v[78:79], v[184:185], v[80:81] op_sel_hi:[1,0]
	ds_bpermute_b32 v80, v1, v2 offset:8
	v_pk_mul_f32 v[78:79], v[6:7], v[78:79]
	v_pk_mul_f32 v[76:77], v[4:5], v[76:77]
	global_store_dwordx4 v[74:75], v[76:79], off offset:16 nt
	v_addc_co_u32_e32 v85, vcc, 0, v75, vcc
	s_waitcnt lgkmcnt(0)
	v_pk_mul_f32 v[76:77], v[174:175], v[80:81] op_sel_hi:[1,0]
	v_pk_mul_f32 v[78:79], v[176:177], v[80:81] op_sel_hi:[1,0]
	v_pk_mul_f32 v[76:77], v[8:9], v[76:77]
	v_pk_mul_f32 v[78:79], v[10:11], v[78:79]
	global_store_dwordx4 v[84:85], v[76:79], off nt
	s_mov_b64 s[2:3], 0x4000
	s_nop 0
	v_pk_mul_f32 v[76:77], v[168:169], v[80:81] op_sel_hi:[1,0]
	v_pk_mul_f32 v[78:79], v[172:173], v[80:81] op_sel_hi:[1,0]
	ds_bpermute_b32 v80, v1, v2 offset:16
	v_pk_mul_f32 v[78:79], v[6:7], v[78:79]
	v_pk_mul_f32 v[76:77], v[4:5], v[76:77]
	global_store_dwordx4 v[82:83], v[76:79], off offset:16 nt
	v_lshl_add_u64 v[82:83], v[74:75], 0, s[2:3]
	s_movk_i32 s2, 0x4000
	s_waitcnt lgkmcnt(0)
	v_pk_mul_f32 v[76:77], v[162:163], v[80:81] op_sel_hi:[1,0]
	v_pk_mul_f32 v[78:79], v[164:165], v[80:81] op_sel_hi:[1,0]
	v_add_co_u32_e32 v84, vcc, s2, v74
	v_pk_mul_f32 v[78:79], v[10:11], v[78:79]
	v_pk_mul_f32 v[76:77], v[8:9], v[76:77]
	v_addc_co_u32_e32 v85, vcc, 0, v75, vcc
	global_store_dwordx4 v[84:85], v[76:79], off nt
	s_mov_b64 s[2:3], 0x6000
	s_nop 0
	v_pk_mul_f32 v[76:77], v[158:159], v[80:81] op_sel_hi:[1,0]
	v_pk_mul_f32 v[78:79], v[160:161], v[80:81] op_sel_hi:[1,0]
	ds_bpermute_b32 v80, v1, v2 offset:24
	v_pk_mul_f32 v[78:79], v[6:7], v[78:79]
	v_pk_mul_f32 v[76:77], v[4:5], v[76:77]
	global_store_dwordx4 v[82:83], v[76:79], off offset:16 nt
	v_lshl_add_u64 v[82:83], v[74:75], 0, s[2:3]
	s_movk_i32 s2, 0x6000
	s_waitcnt lgkmcnt(0)
	v_pk_mul_f32 v[76:77], v[154:155], v[80:81] op_sel_hi:[1,0]
	v_pk_mul_f32 v[78:79], v[156:157], v[80:81] op_sel_hi:[1,0]
	v_add_co_u32_e32 v84, vcc, s2, v74
	v_pk_mul_f32 v[78:79], v[10:11], v[78:79]
	v_pk_mul_f32 v[76:77], v[8:9], v[76:77]
	v_addc_co_u32_e32 v85, vcc, 0, v75, vcc
	global_store_dwordx4 v[84:85], v[76:79], off nt
	s_mov_b64 s[2:3], 0x8000
	s_nop 0
	v_pk_mul_f32 v[76:77], v[150:151], v[80:81] op_sel_hi:[1,0]
	v_pk_mul_f32 v[78:79], v[152:153], v[80:81] op_sel_hi:[1,0]
	ds_bpermute_b32 v80, v1, v2 offset:32
	v_pk_mul_f32 v[78:79], v[6:7], v[78:79]
	v_pk_mul_f32 v[76:77], v[4:5], v[76:77]
	global_store_dwordx4 v[82:83], v[76:79], off offset:16 nt
	v_lshl_add_u64 v[82:83], v[74:75], 0, s[2:3]
	s_mov_b32 s2, 0x8000
	s_waitcnt lgkmcnt(0)
	v_pk_mul_f32 v[76:77], v[130:131], v[80:81] op_sel_hi:[1,0]
	v_pk_mul_f32 v[78:79], v[132:133], v[80:81] op_sel_hi:[1,0]
	v_add_co_u32_e32 v84, vcc, s2, v74
	v_pk_mul_f32 v[78:79], v[10:11], v[78:79]
	v_pk_mul_f32 v[76:77], v[8:9], v[76:77]
	v_addc_co_u32_e32 v85, vcc, 0, v75, vcc
	global_store_dwordx4 v[84:85], v[76:79], off nt
	s_mov_b64 s[2:3], 0xa000
	s_nop 0
	v_pk_mul_f32 v[76:77], v[126:127], v[80:81] op_sel_hi:[1,0]
	v_pk_mul_f32 v[78:79], v[128:129], v[80:81] op_sel_hi:[1,0]
	ds_bpermute_b32 v80, v1, v2 offset:40
	v_pk_mul_f32 v[78:79], v[6:7], v[78:79]
	v_pk_mul_f32 v[76:77], v[4:5], v[76:77]
	global_store_dwordx4 v[82:83], v[76:79], off offset:16 nt
	v_lshl_add_u64 v[82:83], v[74:75], 0, s[2:3]
	s_mov_b32 s2, 0xa000
	s_waitcnt lgkmcnt(0)
	v_pk_mul_f32 v[76:77], v[122:123], v[80:81] op_sel_hi:[1,0]
	v_pk_mul_f32 v[78:79], v[124:125], v[80:81] op_sel_hi:[1,0]
	v_add_co_u32_e32 v84, vcc, s2, v74
	v_pk_mul_f32 v[78:79], v[10:11], v[78:79]
	v_pk_mul_f32 v[76:77], v[8:9], v[76:77]
	v_addc_co_u32_e32 v85, vcc, 0, v75, vcc
	global_store_dwordx4 v[84:85], v[76:79], off nt
	s_mov_b64 s[2:3], 0xc000
	s_nop 0
	v_pk_mul_f32 v[76:77], v[118:119], v[80:81] op_sel_hi:[1,0]
	v_pk_mul_f32 v[78:79], v[120:121], v[80:81] op_sel_hi:[1,0]
	ds_bpermute_b32 v80, v1, v2 offset:48
	v_pk_mul_f32 v[78:79], v[6:7], v[78:79]
	v_pk_mul_f32 v[76:77], v[4:5], v[76:77]
	global_store_dwordx4 v[82:83], v[76:79], off offset:16 nt
	v_lshl_add_u64 v[82:83], v[74:75], 0, s[2:3]
	s_mov_b32 s2, 0xc000
	s_waitcnt lgkmcnt(0)
	v_pk_mul_f32 v[76:77], v[110:111], v[80:81] op_sel_hi:[1,0]
	v_pk_mul_f32 v[78:79], v[112:113], v[80:81] op_sel_hi:[1,0]
	v_add_co_u32_e32 v84, vcc, s2, v74
	v_pk_mul_f32 v[78:79], v[10:11], v[78:79]
	v_pk_mul_f32 v[76:77], v[8:9], v[76:77]
	v_addc_co_u32_e32 v85, vcc, 0, v75, vcc
	global_store_dwordx4 v[84:85], v[76:79], off nt
	s_mov_b64 s[2:3], 0xe000
	s_nop 0
	v_pk_mul_f32 v[76:77], v[104:105], v[80:81] op_sel_hi:[1,0]
	v_pk_mul_f32 v[78:79], v[102:103], v[80:81] op_sel_hi:[1,0]
	ds_bpermute_b32 v80, v1, v2 offset:56
	v_pk_mul_f32 v[78:79], v[6:7], v[78:79]
	v_pk_mul_f32 v[76:77], v[4:5], v[76:77]
	global_store_dwordx4 v[82:83], v[76:79], off offset:16 nt
	v_lshl_add_u64 v[82:83], v[74:75], 0, s[2:3]
	s_mov_b32 s2, 0xe000
	s_waitcnt lgkmcnt(0)
	v_pk_mul_f32 v[76:77], v[116:117], v[80:81] op_sel_hi:[1,0]
	v_pk_mul_f32 v[78:79], v[114:115], v[80:81] op_sel_hi:[1,0]
	v_add_co_u32_e32 v84, vcc, s2, v74
	v_pk_mul_f32 v[78:79], v[10:11], v[78:79]
	v_pk_mul_f32 v[76:77], v[8:9], v[76:77]
	v_addc_co_u32_e32 v85, vcc, 0, v75, vcc
	global_store_dwordx4 v[84:85], v[76:79], off nt
	s_mov_b64 s[2:3], 0x80000
	s_nop 0
	v_pk_mul_f32 v[76:77], v[108:109], v[80:81] op_sel_hi:[1,0]
	v_pk_mul_f32 v[78:79], v[106:107], v[80:81] op_sel_hi:[1,0]
	ds_bpermute_b32 v80, v1, v2 offset:64
	v_pk_mul_f32 v[78:79], v[6:7], v[78:79]
	v_pk_mul_f32 v[76:77], v[4:5], v[76:77]
	global_store_dwordx4 v[82:83], v[76:79], off offset:16 nt
	v_lshl_add_u64 v[82:83], v[74:75], 0, s[2:3]
	s_waitcnt lgkmcnt(0)
	v_pk_mul_f32 v[70:71], v[70:71], v[80:81] op_sel_hi:[1,0]
	s_mov_b32 s2, 0x80000
	v_pk_mul_f32 v[76:77], v[134:135], v[80:81] op_sel_hi:[1,0]
	v_pk_mul_f32 v[78:79], v[10:11], v[70:71]
	v_add_co_u32_e32 v70, vcc, s2, v74
	v_pk_mul_f32 v[76:77], v[8:9], v[76:77]
	s_nop 0
	v_addc_co_u32_e32 v71, vcc, 0, v75, vcc
	v_pk_mul_f32 v[72:73], v[72:73], v[80:81] op_sel_hi:[1,0]
	v_pk_mul_f32 v[68:69], v[68:69], v[80:81] op_sel_hi:[1,0]
	global_store_dwordx4 v[70:71], v[76:79], off nt
	v_pk_mul_f32 v[70:71], v[6:7], v[68:69]
	v_pk_mul_f32 v[68:69], v[4:5], v[72:73]
	global_store_dwordx4 v[82:83], v[68:71], off offset:16 nt
	ds_bpermute_b32 v70, v1, v2 offset:72
	s_mov_b64 s[2:3], 0x82000
	v_lshl_add_u64 v[72:73], v[74:75], 0, s[2:3]
	s_mov_b32 s2, 0x82000
	s_waitcnt lgkmcnt(0)
	v_pk_mul_f32 v[62:63], v[62:63], v[70:71] op_sel_hi:[1,0]
	v_pk_mul_f32 v[66:67], v[66:67], v[70:71] op_sel_hi:[1,0]
	v_pk_mul_f32 v[68:69], v[10:11], v[62:63]
	v_add_co_u32_e32 v62, vcc, s2, v74
	v_pk_mul_f32 v[66:67], v[8:9], v[66:67]
	s_nop 0
	v_addc_co_u32_e32 v63, vcc, 0, v75, vcc
	v_pk_mul_f32 v[64:65], v[64:65], v[70:71] op_sel_hi:[1,0]
	v_pk_mul_f32 v[60:61], v[60:61], v[70:71] op_sel_hi:[1,0]
	global_store_dwordx4 v[62:63], v[66:69], off nt
	v_pk_mul_f32 v[62:63], v[6:7], v[60:61]
	v_pk_mul_f32 v[60:61], v[4:5], v[64:65]
	global_store_dwordx4 v[72:73], v[60:63], off offset:16 nt
	ds_bpermute_b32 v62, v1, v2 offset:80
	s_mov_b64 s[2:3], 0x84000
	v_lshl_add_u64 v[64:65], v[74:75], 0, s[2:3]
	s_mov_b32 s2, 0x84000
	s_waitcnt lgkmcnt(0)
	v_pk_mul_f32 v[54:55], v[54:55], v[62:63] op_sel_hi:[1,0]
	v_pk_mul_f32 v[58:59], v[58:59], v[62:63] op_sel_hi:[1,0]
	v_pk_mul_f32 v[60:61], v[10:11], v[54:55]
	v_add_co_u32_e32 v54, vcc, s2, v74
	v_pk_mul_f32 v[58:59], v[8:9], v[58:59]
	s_nop 0
	v_addc_co_u32_e32 v55, vcc, 0, v75, vcc
	v_pk_mul_f32 v[56:57], v[56:57], v[62:63] op_sel_hi:[1,0]
	v_pk_mul_f32 v[52:53], v[52:53], v[62:63] op_sel_hi:[1,0]
	global_store_dwordx4 v[54:55], v[58:61], off nt
	v_pk_mul_f32 v[54:55], v[6:7], v[52:53]
	v_pk_mul_f32 v[52:53], v[4:5], v[56:57]
	global_store_dwordx4 v[64:65], v[52:55], off offset:16 nt
	ds_bpermute_b32 v54, v1, v2 offset:88
	s_mov_b64 s[2:3], 0x86000
	v_lshl_add_u64 v[56:57], v[74:75], 0, s[2:3]
	s_mov_b32 s2, 0x86000
	s_waitcnt lgkmcnt(0)
	v_pk_mul_f32 v[46:47], v[46:47], v[54:55] op_sel_hi:[1,0]
	v_pk_mul_f32 v[50:51], v[50:51], v[54:55] op_sel_hi:[1,0]
	v_pk_mul_f32 v[52:53], v[10:11], v[46:47]
	v_add_co_u32_e32 v46, vcc, s2, v74
	v_pk_mul_f32 v[50:51], v[8:9], v[50:51]
	s_nop 0
	v_addc_co_u32_e32 v47, vcc, 0, v75, vcc
	v_pk_mul_f32 v[48:49], v[48:49], v[54:55] op_sel_hi:[1,0]
	v_pk_mul_f32 v[44:45], v[44:45], v[54:55] op_sel_hi:[1,0]
	global_store_dwordx4 v[46:47], v[50:53], off nt
	v_pk_mul_f32 v[46:47], v[6:7], v[44:45]
	v_pk_mul_f32 v[44:45], v[4:5], v[48:49]
	global_store_dwordx4 v[56:57], v[44:47], off offset:16 nt
	ds_bpermute_b32 v46, v1, v2 offset:96
	s_mov_b64 s[2:3], 0x88000
	v_lshl_add_u64 v[48:49], v[74:75], 0, s[2:3]
	s_mov_b32 s2, 0x88000
	s_waitcnt lgkmcnt(0)
	v_pk_mul_f32 v[38:39], v[38:39], v[46:47] op_sel_hi:[1,0]
	v_pk_mul_f32 v[42:43], v[42:43], v[46:47] op_sel_hi:[1,0]
	v_pk_mul_f32 v[44:45], v[10:11], v[38:39]
	v_add_co_u32_e32 v38, vcc, s2, v74
	v_pk_mul_f32 v[42:43], v[8:9], v[42:43]
	s_nop 0
	v_addc_co_u32_e32 v39, vcc, 0, v75, vcc
	v_pk_mul_f32 v[40:41], v[40:41], v[46:47] op_sel_hi:[1,0]
	v_pk_mul_f32 v[36:37], v[36:37], v[46:47] op_sel_hi:[1,0]
	global_store_dwordx4 v[38:39], v[42:45], off nt
	v_pk_mul_f32 v[38:39], v[6:7], v[36:37]
	v_pk_mul_f32 v[36:37], v[4:5], v[40:41]
	global_store_dwordx4 v[48:49], v[36:39], off offset:16 nt
	ds_bpermute_b32 v38, v1, v2 offset:104
	s_mov_b64 s[2:3], 0x8a000
	v_lshl_add_u64 v[40:41], v[74:75], 0, s[2:3]
	s_mov_b32 s2, 0x8a000
	s_waitcnt lgkmcnt(0)
	v_pk_mul_f32 v[30:31], v[30:31], v[38:39] op_sel_hi:[1,0]
	v_pk_mul_f32 v[34:35], v[34:35], v[38:39] op_sel_hi:[1,0]
	v_pk_mul_f32 v[36:37], v[10:11], v[30:31]
	v_add_co_u32_e32 v30, vcc, s2, v74
	v_pk_mul_f32 v[34:35], v[8:9], v[34:35]
	s_nop 0
	v_addc_co_u32_e32 v31, vcc, 0, v75, vcc
	v_pk_mul_f32 v[32:33], v[32:33], v[38:39] op_sel_hi:[1,0]
	v_pk_mul_f32 v[28:29], v[28:29], v[38:39] op_sel_hi:[1,0]
	global_store_dwordx4 v[30:31], v[34:37], off nt
	v_pk_mul_f32 v[30:31], v[6:7], v[28:29]
	v_pk_mul_f32 v[28:29], v[4:5], v[32:33]
	global_store_dwordx4 v[40:41], v[28:31], off offset:16 nt
	ds_bpermute_b32 v30, v1, v2 offset:112
	ds_bpermute_b32 v2, v1, v2 offset:120
	s_mov_b64 s[2:3], 0x8c000
	v_lshl_add_u64 v[32:33], v[74:75], 0, s[2:3]
	s_mov_b32 s2, 0x8c000
	s_waitcnt lgkmcnt(1)
	v_pk_mul_f32 v[22:23], v[22:23], v[30:31] op_sel_hi:[1,0]
	s_waitcnt lgkmcnt(0)
	v_pk_mul_f32 v[14:15], v[14:15], v[2:3] op_sel_hi:[1,0]
	v_pk_mul_f32 v[28:29], v[10:11], v[22:23]
	v_add_co_u32_e32 v22, vcc, s2, v74
	v_pk_mul_f32 v[26:27], v[26:27], v[30:31] op_sel_hi:[1,0]
	s_nop 0
	v_addc_co_u32_e32 v23, vcc, 0, v75, vcc
	v_pk_mul_f32 v[18:19], v[18:19], v[2:3] op_sel_hi:[1,0]
	v_pk_mul_f32 v[10:11], v[10:11], v[14:15]
	v_add_co_u32_e32 v14, vcc, 0x8e000, v74
	v_pk_mul_f32 v[26:27], v[8:9], v[26:27]
	v_pk_mul_f32 v[24:25], v[24:25], v[30:31] op_sel_hi:[1,0]
	v_pk_mul_f32 v[20:21], v[20:21], v[30:31] op_sel_hi:[1,0]
	v_pk_mul_f32 v[8:9], v[8:9], v[18:19]
	v_addc_co_u32_e32 v15, vcc, 0, v75, vcc
	global_store_dwordx4 v[22:23], v[26:29], off nt
	v_pk_mul_f32 v[22:23], v[6:7], v[20:21]
	v_pk_mul_f32 v[20:21], v[4:5], v[24:25]
	s_mov_b64 s[2:3], 0x8e000
	global_store_dwordx4 v[14:15], v[8:11], off nt
	global_store_dwordx4 v[32:33], v[20:23], off offset:16 nt
	s_nop 0
	v_pk_mul_f32 v[8:9], v[16:17], v[2:3] op_sel_hi:[1,0]
	v_pk_mul_f32 v[10:11], v[12:13], v[2:3] op_sel_hi:[1,0]
	v_lshl_add_u64 v[20:21], v[74:75], 0, s[2:3]
	v_pk_mul_f32 v[6:7], v[6:7], v[10:11]
	v_pk_mul_f32 v[4:5], v[4:5], v[8:9]
	global_store_dwordx4 v[20:21], v[4:7], off offset:16 nt
